# v27 plus third-branch sample-row merge split-K loads requested together
# speedup vs baseline: 1.0135x; 1.0010x over previous
; #define LAS __attribute__((address_space(3)))
; __device__ __forceinline__ int fresh_bid() { int t = blockIdx.x; asm volatile("" : "+s"(t)); return t; }
; __device__ __forceinline__ void skinny_merge(ParamsK p, int l, LAS unsigned char* lds) {
;     ...
;     for (int piece = fresh_bid(); piece < 256; piece += gridDim.x) {
;         const int rh = piece & 1, cg = piece >> 1;
; #pragma unroll
;         for (int z = 0; z < 3; ++z) {
;             const bf16_t* A = (const bf16_t*)(p->ws + (z == 0 ? WS_AS5 : (z == 1 ? WS_AGLA : WS_ARET)));
;             const bf16_t* Wt = (const bf16_t*)(p->ws + (z == 0 ? WS_WS5O : (z == 1 ? WS_WGLAO : WS_WRETO)) + l * SZ_WBR);
;             const bf16_t* ap = A + (size_t)(NPROMPT + rh * 64 + r) * 1024 + q * 8 + w * 128;
;             const bf16_t* bp = Wt + (size_t)(cg * 16 + r) * 1024 + q * 8 + w * 128;
;             f32x4 acc[4];
; #pragma unroll
;             for (int mt = 0; mt < 4; ++mt) acc[mt] = (f32x4){0.f, 0.f, 0.f, 0.f};
; #pragma unroll
;             for (int ks = 0; ks < 4; ++ks) {
;                 const bf16x8 b = *(const bf16x8*)(bp + ks * 32);
; #pragma unroll
;                 for (int mt = 0; mt < 4; ++mt) { const bf16x8 a = *(const bf16x8*)(ap + (size_t)mt * 16 * 1024 + ks * 32); acc[mt] = __builtin_amdgcn_mfma_f32_16x16x32_bf16(a, b, acc[mt], 0, 0, 0); }
;             }
; #pragma unroll
;             for (int mt = 0; mt < 4; ++mt) *(LAS f32x4*)(red + (z * 8 + w) * 1024 + (mt * 64 + lane) * 4) = acc[mt];
;         }
.LBB0_1271:
	s_and_b32 s10, s8, 1
	v_lshl_or_b32 v0, s10, 17, v73
	s_and_b32 s11, s9, -16
	v_lshl_add_u64 v[2:3], s[0:1], 0, v[0:1]
	v_or_b32_e32 v4, s11, v46
	v_mov_b32_e32 v27, v1
	v_ashrrev_i32_e32 v5, 31, v4
	v_lshl_add_u64 v[2:3], v[2:3], 0, v[26:27]
	v_lshlrev_b64 v[4:5], 11, v[4:5]
	v_lshl_add_u64 v[2:3], v[22:23], 1, v[2:3]
	s_mov_b64 s[12:13], 0x290a0000
	v_lshl_add_u64 v[4:5], v[24:25], 0, v[4:5]
	v_lshl_add_u64 v[36:37], v[2:3], 0, s[12:13]
	s_mov_b32 s12, 0x7600000
	v_add_co_u32_e32 v38, vcc, s12, v4
	s_mov_b32 s12, 0x290a0000
	s_nop 0
	v_addc_co_u32_e32 v39, vcc, 0, v5, vcc
	v_add_co_u32_e32 v10, vcc, s12, v2
	s_mov_b32 s12, 0x290a8000
	s_nop 0
	v_addc_co_u32_e32 v11, vcc, 0, v3, vcc
	v_add_co_u32_e32 v40, vcc, s12, v2
	s_mov_b32 s12, 0x290b0000
	s_nop 0
	v_addc_co_u32_e32 v41, vcc, 0, v3, vcc
	v_add_co_u32_e32 v42, vcc, s12, v2
	s_mov_b32 s12, 0x290b8000
	s_nop 0
	v_addc_co_u32_e32 v43, vcc, 0, v3, vcc
	v_add_co_u32_e32 v44, vcc, s12, v2
	global_load_dwordx4 v[6:9], v[38:39], off
	s_nop 0
	v_addc_co_u32_e32 v45, vcc, 0, v3, vcc
	global_load_dwordx4 v[10:13], v[10:11], off
	s_mov_b64 s[12:13], 0x2a120000
	global_load_dwordx4 v[14:17], v[40:41], off
	global_load_dwordx4 v[18:21], v[42:43], off
	global_load_dwordx4 v[28:31], v[44:45], off
	global_load_dwordx4 v[76:79], v[38:39], off offset:64
	global_load_dwordx4 v[80:83], v[36:37], off offset:64
	global_load_dwordx4 v[84:87], v[40:41], off offset:64
	global_load_dwordx4 v[88:91], v[42:43], off offset:64
	global_load_dwordx4 v[92:95], v[44:45], off offset:64
	global_load_dwordx4 v[96:99], v[38:39], off offset:128
	global_load_dwordx4 v[100:103], v[36:37], off offset:128
	global_load_dwordx4 v[104:107], v[40:41], off offset:128
	global_load_dwordx4 v[108:111], v[42:43], off offset:128
	global_load_dwordx4 v[112:115], v[44:45], off offset:128
	global_load_dwordx4 v[116:119], v[38:39], off offset:192
	global_load_dwordx4 v[120:123], v[36:37], off offset:192
	global_load_dwordx4 v[124:127], v[40:41], off offset:192
	global_load_dwordx4 v[128:131], v[42:43], off offset:192
	global_load_dwordx4 v[132:135], v[44:45], off offset:192
	v_lshl_or_b32 v0, s10, 6, v53
	s_add_i32 s8, s8, s74
	s_add_i32 s9, s9, s97
	s_cmpk_lt_i32 s8, 0x100
	s_waitcnt vmcnt(18)
	v_mfma_f32_16x16x32_bf16 v[10:13], v[10:13], v[6:9], 0
	s_waitcnt vmcnt(17)
	v_mfma_f32_16x16x32_bf16 v[14:17], v[14:17], v[6:9], 0
	s_waitcnt vmcnt(16)
	v_mfma_f32_16x16x32_bf16 v[18:21], v[18:21], v[6:9], 0
	s_waitcnt vmcnt(15)
	v_mfma_f32_16x16x32_bf16 v[6:9], v[28:31], v[6:9], 0
	s_waitcnt vmcnt(0)
	v_mfma_f32_16x16x32_bf16 v[10:13], v[80:83], v[76:79], v[10:13]
	v_mfma_f32_16x16x32_bf16 v[14:17], v[84:87], v[76:79], v[14:17]
	v_mfma_f32_16x16x32_bf16 v[18:21], v[88:91], v[76:79], v[18:21]
	v_mfma_f32_16x16x32_bf16 v[6:9], v[92:95], v[76:79], v[6:9]
	v_mfma_f32_16x16x32_bf16 v[10:13], v[100:103], v[96:99], v[10:13]
	v_mfma_f32_16x16x32_bf16 v[14:17], v[104:107], v[96:99], v[14:17]
	v_mfma_f32_16x16x32_bf16 v[18:21], v[108:111], v[96:99], v[18:21]
	v_mfma_f32_16x16x32_bf16 v[6:9], v[112:115], v[96:99], v[6:9]
	v_mfma_f32_16x16x32_bf16 v[10:13], v[120:123], v[116:119], v[10:13]
	v_mfma_f32_16x16x32_bf16 v[14:17], v[124:127], v[116:119], v[14:17]
	v_mfma_f32_16x16x32_bf16 v[18:21], v[128:131], v[116:119], v[18:21]
	v_mfma_f32_16x16x32_bf16 v[6:9], v[132:135], v[116:119], v[6:9]
	s_nop 7
	ds_write_b128 v47, v[10:13]
	s_nop 0
	ds_write_b128 v47, v[14:17] offset:1024
	s_nop 1
	ds_write_b128 v47, v[18:21] offset:2048
	s_nop 1
	ds_write_b128 v47, v[6:9] offset:3072
	v_add_co_u32_e32 v20, vcc, s14, v4
	v_lshl_add_u64 v[6:7], v[2:3], 0, s[12:13]
	s_nop 0
	v_addc_co_u32_e32 v21, vcc, 0, v5, vcc
	s_mov_b32 s12, 0x2a120000
	v_add_co_u32_e32 v12, vcc, s12, v2
	s_mov_b32 s12, 0x2a128000
	s_nop 0
	v_addc_co_u32_e32 v13, vcc, 0, v3, vcc
	v_add_co_u32_e32 v40, vcc, s12, v2
	s_mov_b32 s12, 0x2a130000
	s_nop 0
	v_addc_co_u32_e32 v41, vcc, 0, v3, vcc
	v_add_co_u32_e32 v42, vcc, s12, v2
	s_mov_b32 s12, 0x2a138000
	s_nop 0
	v_addc_co_u32_e32 v43, vcc, 0, v3, vcc
	v_add_co_u32_e32 v44, vcc, s12, v2
	global_load_dwordx4 v[8:11], v[20:21], off
	s_nop 0
	v_addc_co_u32_e32 v45, vcc, 0, v3, vcc
	global_load_dwordx4 v[12:15], v[12:13], off
	s_mov_b64 s[12:13], 0x2b1a0000
	global_load_dwordx4 v[16:19], v[40:41], off
	global_load_dwordx4 v[28:31], v[42:43], off
	global_load_dwordx4 v[32:35], v[44:45], off
	global_load_dwordx4 v[76:79], v[20:21], off offset:64
	global_load_dwordx4 v[80:83], v[6:7], off offset:64
	global_load_dwordx4 v[84:87], v[40:41], off offset:64
	global_load_dwordx4 v[88:91], v[42:43], off offset:64
	global_load_dwordx4 v[92:95], v[44:45], off offset:64
	global_load_dwordx4 v[96:99], v[20:21], off offset:128
	global_load_dwordx4 v[100:103], v[6:7], off offset:128
	global_load_dwordx4 v[104:107], v[40:41], off offset:128
	global_load_dwordx4 v[108:111], v[42:43], off offset:128
	global_load_dwordx4 v[112:115], v[44:45], off offset:128
	global_load_dwordx4 v[116:119], v[20:21], off offset:192
	global_load_dwordx4 v[120:123], v[6:7], off offset:192
	global_load_dwordx4 v[124:127], v[40:41], off offset:192
	global_load_dwordx4 v[128:131], v[42:43], off offset:192
	global_load_dwordx4 v[132:135], v[44:45], off offset:192
	s_waitcnt vmcnt(18)
	v_mfma_f32_16x16x32_bf16 v[12:15], v[12:15], v[8:11], 0
	s_waitcnt vmcnt(17)
	v_mfma_f32_16x16x32_bf16 v[16:19], v[16:19], v[8:11], 0
	s_waitcnt vmcnt(16)
	v_mfma_f32_16x16x32_bf16 v[28:31], v[28:31], v[8:11], 0
	s_waitcnt vmcnt(15)
	v_mfma_f32_16x16x32_bf16 v[8:11], v[32:35], v[8:11], 0
	s_waitcnt vmcnt(0)
; #define LAS __attribute__((address_space(3)))
; __device__ __forceinline__ void skinny_merge(ParamsK p, int l, LAS unsigned char* lds) {
;     ...
;         for (int z = 0; z < 3; ++z) {
;             const bf16_t* A = (const bf16_t*)(p->ws + (z == 0 ? WS_AS5 : (z == 1 ? WS_AGLA : WS_ARET)));
;             const bf16_t* Wt = (const bf16_t*)(p->ws + (z == 0 ? WS_WS5O : (z == 1 ? WS_WGLAO : WS_WRETO)) + l * SZ_WBR);
;             const bf16_t* ap = A + (size_t)(NPROMPT + rh * 64 + r) * 1024 + q * 8 + w * 128;
;             const bf16_t* bp = Wt + (size_t)(cg * 16 + r) * 1024 + q * 8 + w * 128;
;             f32x4 acc[4];
; #pragma unroll
;             for (int mt = 0; mt < 4; ++mt) acc[mt] = (f32x4){0.f, 0.f, 0.f, 0.f};
; #pragma unroll
;             for (int ks = 0; ks < 4; ++ks) {
;                 const bf16x8 b = *(const bf16x8*)(bp + ks * 32);
; #pragma unroll
;                 for (int mt = 0; mt < 4; ++mt) { const bf16x8 a = *(const bf16x8*)(ap + (size_t)mt * 16 * 1024 + ks * 32); acc[mt] = __builtin_amdgcn_mfma_f32_16x16x32_bf16(a, b, acc[mt], 0, 0, 0); }
;             }
; #pragma unroll
;             for (int mt = 0; mt < 4; ++mt) *(LAS f32x4*)(red + (z * 8 + w) * 1024 + (mt * 64 + lane) * 4) = acc[mt];
;         }
	v_mfma_f32_16x16x32_bf16 v[12:15], v[80:83], v[76:79], v[12:15]
	v_mfma_f32_16x16x32_bf16 v[16:19], v[84:87], v[76:79], v[16:19]
	v_mfma_f32_16x16x32_bf16 v[28:31], v[88:91], v[76:79], v[28:31]
	v_mfma_f32_16x16x32_bf16 v[8:11], v[92:95], v[76:79], v[8:11]
	v_mfma_f32_16x16x32_bf16 v[12:15], v[100:103], v[96:99], v[12:15]
	v_mfma_f32_16x16x32_bf16 v[16:19], v[104:107], v[96:99], v[16:19]
	v_mfma_f32_16x16x32_bf16 v[28:31], v[108:111], v[96:99], v[28:31]
	v_mfma_f32_16x16x32_bf16 v[8:11], v[112:115], v[96:99], v[8:11]
	v_mfma_f32_16x16x32_bf16 v[12:15], v[120:123], v[116:119], v[12:15]
	v_mfma_f32_16x16x32_bf16 v[16:19], v[124:127], v[116:119], v[16:19]
	v_mfma_f32_16x16x32_bf16 v[28:31], v[128:131], v[116:119], v[28:31]
	v_mfma_f32_16x16x32_bf16 v[6:9], v[132:135], v[116:119], v[8:11]
	s_nop 2
	v_lshl_add_u64 v[10:11], v[2:3], 0, s[12:13]
	s_mov_b32 s12, 0x8600000
	v_add_co_u32_e32 v42, vcc, s12, v4
	s_mov_b32 s12, 0x2b1a0000
	s_nop 0
	v_addc_co_u32_e32 v43, vcc, 0, v5, vcc
	ds_write_b128 v47, v[12:15] offset:32768
	ds_write_b128 v47, v[16:19] offset:33792
	ds_write_b128 v47, v[28:31] offset:34816
	ds_write_b128 v47, v[6:9] offset:35840
	v_add_co_u32_e32 v8, vcc, s12, v2
	s_mov_b32 s12, 0x2b1a8000
	s_nop 0
	v_addc_co_u32_e32 v9, vcc, 0, v3, vcc
	v_add_co_u32_e32 v28, vcc, s12, v2
	s_mov_b32 s12, 0x2b1b0000
	s_nop 0
	v_addc_co_u32_e32 v29, vcc, 0, v3, vcc
	v_add_co_u32_e32 v30, vcc, s12, v2
	global_load_dwordx4 v[4:7], v[42:43], off
	s_nop 0
	v_addc_co_u32_e32 v31, vcc, 0, v3, vcc
	global_load_dwordx4 v[32:35], v[30:31], off
	s_mov_b32 s12, 0x2b1b8000
	s_waitcnt vmcnt(0)
	v_mfma_f32_16x16x32_bf16 v[34:37], v[32:35], v[4:7], 0
	v_add_co_u32_e32 v32, vcc, s12, v2
	global_load_dwordx4 v[12:15], v[8:9], off
	global_load_dwordx4 v[16:19], v[28:29], off
	v_addc_co_u32_e32 v33, vcc, 0, v3, vcc
	global_load_dwordx4 v[38:41], v[32:33], off
	s_waitcnt vmcnt(2)
	v_mfma_f32_16x16x32_bf16 v[12:15], v[12:15], v[4:7], 0
	s_waitcnt vmcnt(1)
	v_mfma_f32_16x16x32_bf16 v[16:19], v[16:19], v[4:7], 0
	s_waitcnt vmcnt(0)
	v_mfma_f32_16x16x32_bf16 v[2:5], v[38:41], v[4:7], 0
	global_load_dwordx4 v[76:79], v[42:43], off offset:64
	global_load_dwordx4 v[80:83], v[10:11], off offset:64
	global_load_dwordx4 v[84:87], v[28:29], off offset:64
	global_load_dwordx4 v[88:91], v[30:31], off offset:64
	global_load_dwordx4 v[92:95], v[32:33], off offset:64
	global_load_dwordx4 v[96:99], v[42:43], off offset:128
	global_load_dwordx4 v[100:103], v[10:11], off offset:128
	global_load_dwordx4 v[104:107], v[28:29], off offset:128
	global_load_dwordx4 v[108:111], v[30:31], off offset:128
	global_load_dwordx4 v[112:115], v[32:33], off offset:128
	global_load_dwordx4 v[116:119], v[42:43], off offset:192
	global_load_dwordx4 v[120:123], v[10:11], off offset:192
	global_load_dwordx4 v[124:127], v[28:29], off offset:192
	global_load_dwordx4 v[128:131], v[30:31], off offset:192
	global_load_dwordx4 v[132:135], v[32:33], off offset:192
	s_waitcnt vmcnt(0)
	v_mfma_f32_16x16x32_bf16 v[12:15], v[80:83], v[76:79], v[12:15]
	v_mfma_f32_16x16x32_bf16 v[16:19], v[84:87], v[76:79], v[16:19]
	v_mfma_f32_16x16x32_bf16 v[34:37], v[88:91], v[76:79], v[34:37]
	v_mfma_f32_16x16x32_bf16 v[2:5], v[92:95], v[76:79], v[2:5]
	v_mfma_f32_16x16x32_bf16 v[38:41], v[100:103], v[96:99], v[12:15]
	s_nop 2
	v_mfma_f32_16x16x32_bf16 v[18:21], v[104:107], v[96:99], v[16:19]
	v_mfma_f32_16x16x32_bf16 v[14:17], v[108:111], v[96:99], v[34:37]
	s_nop 2
	v_mfma_f32_16x16x32_bf16 v[2:5], v[112:115], v[96:99], v[2:5]
	s_nop 0
	s_nop 0
	v_mfma_f32_16x16x32_bf16 v[10:13], v[120:123], v[116:119], v[38:41]
	v_mfma_f32_16x16x32_bf16 v[14:17], v[128:131], v[116:119], v[14:17]
	v_mfma_f32_16x16x32_bf16 v[18:21], v[124:127], v[116:119], v[18:21]
	v_mfma_f32_16x16x32_bf16 v[2:5], v[132:135], v[116:119], v[2:5]
	s_nop 7
	s_nop 0
	ds_write_b128 v49, v[10:13]
	s_nop 3
	ds_write_b128 v50, v[18:21]
	ds_write_b128 v51, v[14:17]
	ds_write_b128 v52, v[2:5]
	s_waitcnt lgkmcnt(0)
	s_barrier
; __device__ __forceinline__ bf16_t f2bf(float f) { return (bf16_t)(cvt_pk_bf16(f, 0.f) & 0xffffu); }
; __device__ __forceinline__ float bf2f(bf16_t b) { return __uint_as_float(((unsigned)b) << 16); }
; __device__ __forceinline__ void skinny_merge(ParamsK p, int l, LAS unsigned char* lds) {
;     ...
;         __syncthreads();
; #pragma unroll
;         for (int h = 0; h < 2; ++h) {
;             const int e = tid + h * 512;
;             const int mt = e >> 8, ln = (e >> 2) & 63, j = e & 3;
;             const int row = NPROMPT + rh * 64 + mt * 16 + (ln >> 4) * 4 + j, col = cg * 16 + (ln & 15);
;             float tot = 0.f;
; #pragma unroll
;             for (int z = 0; z < 3; ++z) { float sum = 0.f;
; #pragma unroll
;                 for (int ww = 0; ww < 8; ++ww) sum += red[(z * 8 + ww) * 1024 + e];
;                 tot += sum * bf2f(proj[(size_t)row * NIN + OFF_MG + z * 2048 + col]); }
;             O[(size_t)row * DM + col] = f2bf(tot);
;         }
;         __syncthreads();
	ds_read2st64_b32 v[8:9], v55 offset1:8
	v_or_b32_e32 v2, s11, v48
	ds_read2st64_b32 v[10:11], v55 offset0:16 offset1:24
	v_ashrrev_i32_e32 v3, 31, v2
	v_lshlrev_b64 v[2:3], 1, v[2:3]
	v_lshl_add_u64 v[6:7], s[6:7], 0, v[2:3]
	v_add_u32_e32 v4, v0, v54
	v_mad_i64_i32 v[74:75], s[10:11], v4, s73, v[6:7]
	s_waitcnt lgkmcnt(1)
	v_add_f32_e32 v8, 0, v8
	s_waitcnt lgkmcnt(0)
	v_add_f32_e32 v8, v8, v10
	global_load_ushort v10, v[74:75], off
	ds_read2st64_b32 v[12:13], v55 offset0:32 offset1:40
	v_add_co_u32_e32 v74, vcc, s39, v74
	ds_read2st64_b32 v[14:15], v55 offset0:48 offset1:56
	s_nop 0
	v_addc_co_u32_e32 v75, vcc, 0, v75, vcc
	s_waitcnt lgkmcnt(1)
	v_add_f32_e32 v8, v8, v12
	global_load_ushort v12, v[74:75], off offset:-4096
	ds_read2st64_b32 v[16:17], v55 offset0:64 offset1:72
	ds_read2st64_b32 v[18:19], v55 offset0:80 offset1:88
	ds_read2st64_b32 v[20:21], v55 offset0:96 offset1:104
	ds_read2st64_b32 v[28:29], v55 offset0:112 offset1:120
	s_waitcnt lgkmcnt(4)
	v_add_f32_e32 v8, v8, v14
	ds_read2st64_b32 v[30:31], v55 offset0:128 offset1:136
	s_waitcnt lgkmcnt(4)
	v_add_f32_e32 v8, v8, v16
	ds_read2st64_b32 v[32:33], v55 offset0:144 offset1:152
	s_waitcnt lgkmcnt(4)
	v_add_f32_e32 v8, v8, v18
	ds_read2st64_b32 v[34:35], v55 offset0:160 offset1:168
	s_waitcnt lgkmcnt(4)
	v_add_f32_e32 v8, v8, v20
	ds_read2st64_b32 v[36:37], v55 offset0:176 offset1:184
	s_waitcnt lgkmcnt(4)
	v_add_f32_e32 v8, v8, v28
	ds_read2st64_b32 v[38:39], v55 offset0:192 offset1:200
	ds_read2st64_b32 v[40:41], v55 offset0:208 offset1:216
	ds_read2st64_b32 v[42:43], v55 offset0:224 offset1:232
	ds_read2st64_b32 v[44:45], v55 offset0:240 offset1:248
	v_ashrrev_i32_e32 v5, 31, v4
	v_lshl_add_u64 v[2:3], s[4:5], 0, v[2:3]
	v_lshlrev_b64 v[4:5], 12, v[4:5]
	v_lshl_add_u64 v[4:5], v[2:3], 0, v[4:5]
	s_waitcnt vmcnt(1)
	v_lshlrev_b32_e32 v10, 16, v10
	v_fma_f32 v8, v8, v10, 0
	s_waitcnt lgkmcnt(7)
	v_add_f32_e32 v10, 0, v30
	s_waitcnt lgkmcnt(6)
	v_add_f32_e32 v10, v10, v32
	s_waitcnt lgkmcnt(5)
	v_add_f32_e32 v10, v10, v34
	s_waitcnt lgkmcnt(4)
	v_add_f32_e32 v10, v10, v36
	s_waitcnt lgkmcnt(3)
	v_add_f32_e32 v10, v10, v38
	s_waitcnt lgkmcnt(2)
	v_add_f32_e32 v10, v10, v40
	s_waitcnt lgkmcnt(1)
	v_add_f32_e32 v10, v10, v42
	s_waitcnt lgkmcnt(0)
	v_add_f32_e32 v10, v10, v44
	s_waitcnt vmcnt(0)
	v_lshlrev_b32_e32 v12, 16, v12
	v_fmac_f32_e32 v8, v10, v12
	ds_read_b32 v10, v56
	ds_read_b32 v12, v57
	s_waitcnt lgkmcnt(1)
	v_add_f32_e32 v10, 0, v10
	s_waitcnt lgkmcnt(0)
	v_add_f32_e32 v10, v10, v12
	ds_read_b32 v12, v58
	s_waitcnt lgkmcnt(0)
	v_add_f32_e32 v10, v10, v12
	ds_read_b32 v12, v59
	s_waitcnt lgkmcnt(0)
	v_add_f32_e32 v10, v10, v12
	ds_read_b32 v12, v60
	s_waitcnt lgkmcnt(0)
	v_add_f32_e32 v10, v10, v12
	ds_read_b32 v12, v61
	s_waitcnt lgkmcnt(0)
	v_add_f32_e32 v10, v10, v12
	ds_read_b32 v12, v62
	s_waitcnt lgkmcnt(0)
	v_add_f32_e32 v10, v10, v12
	ds_read_b32 v12, v63
	s_waitcnt lgkmcnt(0)
	v_add_f32_e32 v10, v10, v12
	global_load_ushort v12, v[74:75], off
	s_waitcnt vmcnt(0)
	v_lshlrev_b32_e32 v12, 16, v12
	v_fmac_f32_e32 v8, v10, v12
	v_cvt_pk_bf16_f32 v8, v8, s0
	global_store_short v[4:5], v8, off
	v_add_u32_e32 v4, v0, v64
	v_mad_i64_i32 v[6:7], s[10:11], v4, s73, v[6:7]
	global_load_ushort v8, v[6:7], off
	v_add_co_u32_e32 v6, vcc, s39, v6
	v_add_f32_e32 v0, 0, v9
	s_nop 0
	v_addc_co_u32_e32 v7, vcc, 0, v7, vcc
	global_load_ushort v9, v[6:7], off offset:-4096
	v_add_f32_e32 v0, v0, v11
	global_load_ushort v6, v[6:7], off
	v_add_f32_e32 v0, v0, v13
	v_add_f32_e32 v0, v0, v15
	v_add_f32_e32 v0, v0, v17
	v_add_f32_e32 v0, v0, v19
	v_add_f32_e32 v0, v0, v21
	v_add_f32_e32 v0, v0, v29
	v_ashrrev_i32_e32 v5, 31, v4
	v_lshlrev_b64 v[4:5], 12, v[4:5]
	v_lshl_add_u64 v[2:3], v[2:3], 0, v[4:5]
	s_waitcnt vmcnt(2)
	v_lshlrev_b32_e32 v8, 16, v8
	v_fma_f32 v0, v0, v8, 0
	v_add_f32_e32 v8, 0, v31
	v_add_f32_e32 v8, v8, v33
	v_add_f32_e32 v8, v8, v35
	v_add_f32_e32 v8, v8, v37
	v_add_f32_e32 v8, v8, v39
	v_add_f32_e32 v8, v8, v41
	v_add_f32_e32 v8, v8, v43
	v_add_f32_e32 v8, v8, v45
	s_waitcnt vmcnt(1)
	v_lshlrev_b32_e32 v9, 16, v9
	v_fmac_f32_e32 v0, v8, v9
	ds_read_b32 v8, v65
	ds_read_b32 v9, v66
	s_waitcnt vmcnt(0)
	v_lshlrev_b32_e32 v6, 16, v6
	s_waitcnt lgkmcnt(1)
	v_add_f32_e32 v8, 0, v8
	s_waitcnt lgkmcnt(0)
	v_add_f32_e32 v8, v8, v9
	ds_read_b32 v9, v67
	s_waitcnt lgkmcnt(0)
	v_add_f32_e32 v8, v8, v9
	ds_read_b32 v9, v68
	s_waitcnt lgkmcnt(0)
	v_add_f32_e32 v8, v8, v9
	ds_read_b32 v9, v69
	s_waitcnt lgkmcnt(0)
	v_add_f32_e32 v8, v8, v9
	ds_read_b32 v9, v70
	s_waitcnt lgkmcnt(0)
	v_add_f32_e32 v8, v8, v9
	ds_read_b32 v9, v71
	s_waitcnt lgkmcnt(0)
	v_add_f32_e32 v8, v8, v9
	ds_read_b32 v9, v72
	s_waitcnt lgkmcnt(0)
	v_add_f32_e32 v8, v8, v9
	v_fmac_f32_e32 v0, v8, v6
	v_cvt_pk_bf16_f32 v0, v0, s0
	global_store_short v[2:3], v0, off
	s_barrier
	s_cbranch_scc1 .LBB0_1271
